# mid phase rebalanced: the 64 workgroups running the heavy K=4096 compress-GEMM-1 units take no q-up/kv-up units; the other 448 share the 3584 small units, 8 each
# speedup vs baseline: 1.0140x; 1.0120x over previous
.LBB0_1102:
	v_readlane_b32 s2, v255, 26
	s_waitcnt lgkmcnt(0)
	s_add_u32 s14, s0, 0x148e8800
	v_readlane_b32 s3, v255, 27
	s_addc_u32 s15, s1, 0
	s_and_b64 vcc, exec, s[2:3]
	s_cbranch_vccnz .LBB0_1154
	s_cmp_lt_u32 s92, 64
	s_cbranch_scc1 .LBB0_1154
	v_lshlrev_b32_e32 v2, 3, v137
	v_and_b32_e32 v2, 0x78, v2
	v_mov_b32_e32 v3, v0
	s_add_u32 s20, s0, 0x130e8800
	v_lshl_add_u64 v[2:3], s[0:1], 0, v[2:3]
	s_mov_b64 s[2:3], 0x9ad8800
	s_addc_u32 s21, s1, 0
	v_and_b32_e32 v1, 31, v137
	v_lshl_add_u64 v[134:135], v[2:3], 0, s[2:3]
	s_mov_b64 s[2:3], 0x9bd8800
	s_add_u32 s24, s0, 0x19a0000
	v_lshl_add_u64 v[136:137], v[2:3], 0, s[2:3]
	v_lshlrev_b32_e32 v2, 3, v1
	v_mov_b32_e32 v3, v0
	s_addc_u32 s30, s1, 0
	v_lshl_add_u64 v[138:139], s[18:19], 0, v[2:3]
	v_lshlrev_b32_e32 v2, 2, v1
	v_lshrrev_b32_e32 v4, 5, v157
	v_lshl_add_u64 v[2:3], s[0:1], 0, v[2:3]
	s_mov_b64 s[2:3], 0x14ae8900
	s_add_u32 s18, s0, 0x14ae8800
	v_cmp_gt_u32_e64 s[4:5], 16, v1
	v_lshl_add_u32 v133, v156, 7, v218
	v_lshl_add_u64 v[140:141], v[2:3], 0, s[2:3]
	v_or_b32_e32 v161, -16, v4
	s_addc_u32 s19, s1, 0
	s_sub_i32 s31, s92, 64
	s_branch .LBB0_1105
.LBB0_1104:
	s_addk_i32 s31, 0x1c0
	s_cmpk_gt_i32 s31, 0x5ff
	s_barrier
	s_cbranch_scc1 .LBB0_1154

.LBB0_1154:
	v_readlane_b32 s2, v255, 24
	v_readlane_b32 s3, v255, 25
	s_and_b64 vcc, exec, s[2:3]
	s_cbranch_vccnz .LBB0_1209
	s_cmp_lt_u32 s92, 64
	s_cbranch_scc1 .LBB0_1209
	s_add_u32 s10, s0, 0x140e8800
	s_addc_u32 s11, s1, 0
	s_add_u32 s24, s0, 0x1b20000
	s_addc_u32 s28, s1, 0
	s_add_u32 s12, s0, 0x1aae8800
	s_addc_u32 s13, s1, 0
	s_add_u32 s0, s0, 0x17ae8800
	s_addc_u32 s1, s1, 0
	s_sub_i32 s31, s92, 0x100
	s_add_i32 s30, s92, 0xc0
	s_cmp_lt_u32 s92, 0x100
	s_cselect_b32 s31, s30, s31
	s_mov_b32 s30, s31
	s_lshl_b32 s29, s31, 3
	s_branch .LBB0_1157
.LBB0_1156:
	v_readlane_b32 s2, v254, 63
	s_addk_i32 s31, 0x1c0
	s_addk_i32 s30, 0x1c0
	s_addk_i32 s29, 0xe00
	s_cmpk_lt_i32 s31, 0x800
	s_barrier
	s_cbranch_scc0 .LBB0_1209
